# grid barrier: non-leader blocks spin on the top-level generation word instead of the per-XCD word bumped later by the XCD leader
# baseline (speedup 1.0000x reference)
; __device__ __forceinline__ unsigned xb_ld(unsigned* q) { return __hip_atomic_load(q, __ATOMIC_RELAXED, __HIP_MEMORY_SCOPE_AGENT); }
; __device__ __forceinline__ unsigned xb_add(unsigned* q, unsigned v) { return __hip_atomic_fetch_add(q, v, __ATOMIC_RELAXED, __HIP_MEMORY_SCOPE_AGENT); }
; #define XB_SPIN(cond, bar) do { unsigned _sp = 0; while (cond) { __builtin_amdgcn_s_sleep(1); \
;     if ((++_sp & 255u) == 0u) { if (xb_ld(&(bar)[XB_TMO])) break; if (_sp > XB_SPIN_CAP) { atomicAdd(&(bar)[XB_TMO], 1u); break; } } } } while (0)
; __device__ __forceinline__ void gbar(unsigned* bar, volatile unsigned* st) {
;     ...
;     const unsigned old = xb_add(&bar[XB_XSUB(x)], 1u);
;     const unsigned gen = old / nloc;
;     if (old + 1u == (gen + 1u) * nloc) {
;       __builtin_amdgcn_fence(__ATOMIC_RELEASE, "agent");
;       asm volatile("s_waitcnt vmcnt(0)" ::: "memory");
;       const unsigned og = xb_add(&bar[XB_TOP], 1u);
;       const unsigned tg = og / nx;
;       if (og + 1u == (tg + 1u) * nx) xb_add(&bar[XB_TOPGEN], 1u);
;       else XB_SPIN(xb_ld(&bar[XB_TOPGEN]) == tg, bar);
;       __builtin_amdgcn_fence(__ATOMIC_ACQUIRE, "agent");
;       xb_add(&bar[XB_XGEN(x)], 1u);
;       asm volatile("s_waitcnt vmcnt(0)" ::: "memory");
;     } else {
;       XB_SPIN(xb_ld(&bar[XB_XGEN(x)]) == gen, bar);
.LBB0_79:
	s_or_b64 exec, exec, s[12:13]
	v_cvt_f32_u32_e32 v4, v2
	s_waitcnt vmcnt(0)
	v_readfirstlane_b32 s2, v3
	v_rcp_iflag_f32_e32 v4, v4
	s_nop 0
	v_add_u32_e32 v1, s2, v1
	v_add_u32_e32 v5, 1, v1
	v_mul_f32_e32 v3, 0x4f7ffffe, v4
	v_cvt_u32_f32_e32 v3, v3
	v_sub_u32_e32 v4, 0, v2
	v_mul_lo_u32 v4, v4, v3
	v_mul_hi_u32 v4, v3, v4
	v_add_u32_e32 v3, v3, v4
	v_mul_hi_u32 v3, v1, v3
	v_mul_lo_u32 v4, v3, v2
	v_sub_u32_e32 v1, v1, v4
	v_add_u32_e32 v6, 1, v3
	v_cmp_ge_u32_e32 vcc, v1, v2
	v_sub_u32_e32 v4, v1, v2
	s_nop 0
	v_cndmask_b32_e32 v3, v3, v6, vcc
	v_cndmask_b32_e32 v1, v1, v4, vcc
	v_add_u32_e32 v4, 1, v3
	v_cmp_ge_u32_e32 vcc, v1, v2
	s_nop 1
	v_cndmask_b32_e32 v1, v3, v4, vcc
	v_mad_u64_u32 v[2:3], s[2:3], v2, v1, v[2:3]
	v_cmp_ne_u32_e32 vcc, v5, v2
	s_and_saveexec_b64 s[2:3], vcc
	s_xor_b64 s[10:11], exec, s[2:3]
	s_cbranch_execz .LBB0_93
	v_mov_b32_e32 v0, 0
	s_add_u32 s14, s6, 0x3500
	s_addc_u32 s15, s7, 0
	global_load_dword v0, v0, s[14:15] sc1
	s_waitcnt vmcnt(0)
	v_cmp_eq_u32_e32 vcc, v0, v1
	s_and_saveexec_b64 s[12:13], vcc
	s_cbranch_execz .LBB0_92
	s_mov_b32 s2, 1
	s_mov_b64 s[16:17], 0
	v_mov_b32_e32 v0, 0
	s_branch .LBB0_83

; __device__ __forceinline__ unsigned xb_ld(unsigned* q) { return __hip_atomic_load(q, __ATOMIC_RELAXED, __HIP_MEMORY_SCOPE_AGENT); }
; __device__ __forceinline__ unsigned xb_add(unsigned* q, unsigned v) { return __hip_atomic_fetch_add(q, v, __ATOMIC_RELAXED, __HIP_MEMORY_SCOPE_AGENT); }
; #define XB_SPIN(cond, bar) do { unsigned _sp = 0; while (cond) { __builtin_amdgcn_s_sleep(1); \
;     if ((++_sp & 255u) == 0u) { if (xb_ld(&(bar)[XB_TMO])) break; if (_sp > XB_SPIN_CAP) { atomicAdd(&(bar)[XB_TMO], 1u); break; } } } } while (0)
; __device__ __forceinline__ void gbar(unsigned* bar, volatile unsigned* st) {
;     ...
;     const unsigned old = xb_add(&bar[XB_XSUB(x)], 1u);
;     const unsigned gen = old / nloc;
;     if (old + 1u == (gen + 1u) * nloc) {
;       __builtin_amdgcn_fence(__ATOMIC_RELEASE, "agent");
;       asm volatile("s_waitcnt vmcnt(0)" ::: "memory");
;       const unsigned og = xb_add(&bar[XB_TOP], 1u);
;       const unsigned tg = og / nx;
;       if (og + 1u == (tg + 1u) * nx) xb_add(&bar[XB_TOPGEN], 1u);
;       else XB_SPIN(xb_ld(&bar[XB_TOPGEN]) == tg, bar);
;       __builtin_amdgcn_fence(__ATOMIC_ACQUIRE, "agent");
;       xb_add(&bar[XB_XGEN(x)], 1u);
;       asm volatile("s_waitcnt vmcnt(0)" ::: "memory");
;     } else {
;       XB_SPIN(xb_ld(&bar[XB_XGEN(x)]) == gen, bar);
.LBB0_140:
	s_or_b64 exec, exec, s[24:25]
	s_waitcnt vmcnt(0)
	v_readfirstlane_b32 s19, v20
	v_sub_u32_e32 v21, 0, v2
	s_nop 0
	v_add_u32_e32 v20, s19, v3
	v_cvt_f32_u32_e32 v3, v2
	v_rcp_iflag_f32_e32 v3, v3
	s_nop 0
	v_mul_f32_e32 v3, 0x4f7ffffe, v3
	v_cvt_u32_f32_e32 v3, v3
	v_mul_lo_u32 v21, v21, v3
	v_mul_hi_u32 v21, v3, v21
	v_add_u32_e32 v3, v3, v21
	v_mul_hi_u32 v3, v20, v3
	v_mul_lo_u32 v21, v3, v2
	v_sub_u32_e32 v21, v20, v21
	v_cmp_ge_u32_e32 vcc, v21, v2
	v_add_u32_e32 v22, 1, v3
	s_nop 0
	v_cndmask_b32_e32 v3, v3, v22, vcc
	v_sub_u32_e32 v22, v21, v2
	v_cndmask_b32_e32 v21, v21, v22, vcc
	v_cmp_ge_u32_e32 vcc, v21, v2
	v_add_u32_e32 v21, 1, v3
	v_add_u32_e32 v22, 1, v20
	v_cndmask_b32_e32 v3, v3, v21, vcc
	v_mad_u64_u32 v[20:21], s[22:23], v2, v3, v[2:3]
	v_cmp_ne_u32_e32 vcc, v22, v20
	s_and_saveexec_b64 s[22:23], vcc
	s_xor_b64 s[22:23], exec, s[22:23]
	s_cbranch_execz .LBB0_154
	s_add_u32 s26, s10, 0x3500
	s_addc_u32 s27, s11, 0
	global_load_dword v0, v1, s[26:27] sc1
	s_waitcnt vmcnt(0)
	v_cmp_eq_u32_e32 vcc, v0, v3
	s_and_saveexec_b64 s[24:25], vcc
	s_cbranch_execz .LBB0_153
	s_mov_b32 s19, 1
	s_mov_b64 s[28:29], 0
	s_branch .LBB0_144

; __device__ __forceinline__ unsigned xb_ld(unsigned* q) { return __hip_atomic_load(q, __ATOMIC_RELAXED, __HIP_MEMORY_SCOPE_AGENT); }
; __device__ __forceinline__ unsigned xb_add(unsigned* q, unsigned v) { return __hip_atomic_fetch_add(q, v, __ATOMIC_RELAXED, __HIP_MEMORY_SCOPE_AGENT); }
; #define XB_SPIN(cond, bar) do { unsigned _sp = 0; while (cond) { __builtin_amdgcn_s_sleep(1); \
;     if ((++_sp & 255u) == 0u) { if (xb_ld(&(bar)[XB_TMO])) break; if (_sp > XB_SPIN_CAP) { atomicAdd(&(bar)[XB_TMO], 1u); break; } } } } while (0)
; __device__ __forceinline__ void gbar(unsigned* bar, volatile unsigned* st) {
;     ...
;     const unsigned old = xb_add(&bar[XB_XSUB(x)], 1u);
;     const unsigned gen = old / nloc;
;     if (old + 1u == (gen + 1u) * nloc) {
;       __builtin_amdgcn_fence(__ATOMIC_RELEASE, "agent");
;       asm volatile("s_waitcnt vmcnt(0)" ::: "memory");
;       const unsigned og = xb_add(&bar[XB_TOP], 1u);
;       const unsigned tg = og / nx;
;       if (og + 1u == (tg + 1u) * nx) xb_add(&bar[XB_TOPGEN], 1u);
;       else XB_SPIN(xb_ld(&bar[XB_TOPGEN]) == tg, bar);
;       __builtin_amdgcn_fence(__ATOMIC_ACQUIRE, "agent");
;       xb_add(&bar[XB_XGEN(x)], 1u);
;       asm volatile("s_waitcnt vmcnt(0)" ::: "memory");
;     } else {
;       XB_SPIN(xb_ld(&bar[XB_XGEN(x)]) == gen, bar);
.LBB0_199:
	s_or_b64 exec, exec, s[24:25]
	s_waitcnt vmcnt(0)
	v_readfirstlane_b32 s22, v20
	v_sub_u32_e32 v21, 0, v2
	s_nop 0
	v_add_u32_e32 v20, s22, v3
	v_cvt_f32_u32_e32 v3, v2
	v_rcp_iflag_f32_e32 v3, v3
	s_nop 0
	v_mul_f32_e32 v3, 0x4f7ffffe, v3
	v_cvt_u32_f32_e32 v3, v3
	v_mul_lo_u32 v21, v21, v3
	v_mul_hi_u32 v21, v3, v21
	v_add_u32_e32 v3, v3, v21
	v_mul_hi_u32 v3, v20, v3
	v_mul_lo_u32 v21, v3, v2
	v_sub_u32_e32 v21, v20, v21
	v_cmp_ge_u32_e32 vcc, v21, v2
	v_add_u32_e32 v22, 1, v3
	s_nop 0
	v_cndmask_b32_e32 v3, v3, v22, vcc
	v_sub_u32_e32 v22, v21, v2
	v_cndmask_b32_e32 v21, v21, v22, vcc
	v_cmp_ge_u32_e32 vcc, v21, v2
	v_add_u32_e32 v21, 1, v3
	v_add_u32_e32 v22, 1, v20
	v_cndmask_b32_e32 v3, v3, v21, vcc
	v_mad_u64_u32 v[20:21], s[22:23], v2, v3, v[2:3]
	v_cmp_ne_u32_e32 vcc, v22, v20
	s_and_saveexec_b64 s[22:23], vcc
	s_xor_b64 s[22:23], exec, s[22:23]
	s_cbranch_execz .LBB0_213
	s_add_u32 s26, s10, 0x3500
	s_addc_u32 s27, s11, 0
	global_load_dword v0, v1, s[26:27] sc1
	s_waitcnt vmcnt(0)
	v_cmp_eq_u32_e32 vcc, v0, v3
	s_and_saveexec_b64 s[24:25], vcc
	s_cbranch_execz .LBB0_212
	s_mov_b32 s40, 1
	s_mov_b64 s[28:29], 0
	s_branch .LBB0_203

; __device__ __forceinline__ unsigned xb_ld(unsigned* q) { return __hip_atomic_load(q, __ATOMIC_RELAXED, __HIP_MEMORY_SCOPE_AGENT); }
; __device__ __forceinline__ unsigned xb_add(unsigned* q, unsigned v) { return __hip_atomic_fetch_add(q, v, __ATOMIC_RELAXED, __HIP_MEMORY_SCOPE_AGENT); }
; #define XB_SPIN(cond, bar) do { unsigned _sp = 0; while (cond) { __builtin_amdgcn_s_sleep(1); \
;     if ((++_sp & 255u) == 0u) { if (xb_ld(&(bar)[XB_TMO])) break; if (_sp > XB_SPIN_CAP) { atomicAdd(&(bar)[XB_TMO], 1u); break; } } } } while (0)
; __device__ __forceinline__ void gbar(unsigned* bar, volatile unsigned* st) {
;     ...
;     const unsigned old = xb_add(&bar[XB_XSUB(x)], 1u);
;     const unsigned gen = old / nloc;
;     if (old + 1u == (gen + 1u) * nloc) {
;       __builtin_amdgcn_fence(__ATOMIC_RELEASE, "agent");
;       asm volatile("s_waitcnt vmcnt(0)" ::: "memory");
;       const unsigned og = xb_add(&bar[XB_TOP], 1u);
;       const unsigned tg = og / nx;
;       if (og + 1u == (tg + 1u) * nx) xb_add(&bar[XB_TOPGEN], 1u);
;       else XB_SPIN(xb_ld(&bar[XB_TOPGEN]) == tg, bar);
;       __builtin_amdgcn_fence(__ATOMIC_ACQUIRE, "agent");
;       xb_add(&bar[XB_XGEN(x)], 1u);
;       asm volatile("s_waitcnt vmcnt(0)" ::: "memory");
;     } else {
;       XB_SPIN(xb_ld(&bar[XB_XGEN(x)]) == gen, bar);
.LBB0_256:
	s_or_b64 exec, exec, s[22:23]
	s_waitcnt vmcnt(0)
	v_readfirstlane_b32 s19, v20
	v_sub_u32_e32 v21, 0, v2
	s_nop 0
	v_add_u32_e32 v20, s19, v3
	v_cvt_f32_u32_e32 v3, v2
	v_rcp_iflag_f32_e32 v3, v3
	s_nop 0
	v_mul_f32_e32 v3, 0x4f7ffffe, v3
	v_cvt_u32_f32_e32 v3, v3
	v_mul_lo_u32 v21, v21, v3
	v_mul_hi_u32 v21, v3, v21
	v_add_u32_e32 v3, v3, v21
	v_mul_hi_u32 v3, v20, v3
	v_mul_lo_u32 v21, v3, v2
	v_sub_u32_e32 v21, v20, v21
	v_cmp_ge_u32_e32 vcc, v21, v2
	v_add_u32_e32 v22, 1, v3
	s_nop 0
	v_cndmask_b32_e32 v3, v3, v22, vcc
	v_sub_u32_e32 v22, v21, v2
	v_cndmask_b32_e32 v21, v21, v22, vcc
	v_cmp_ge_u32_e32 vcc, v21, v2
	v_add_u32_e32 v21, 1, v3
	v_add_u32_e32 v22, 1, v20
	v_cndmask_b32_e32 v3, v3, v21, vcc
	v_mad_u64_u32 v[20:21], s[20:21], v2, v3, v[2:3]
	v_cmp_ne_u32_e32 vcc, v22, v20
	s_and_saveexec_b64 s[20:21], vcc
	s_xor_b64 s[20:21], exec, s[20:21]
	s_cbranch_execz .LBB0_270
	s_add_u32 s24, s8, 0x3500
	s_addc_u32 s25, s9, 0
	global_load_dword v0, v1, s[24:25] sc1
	s_waitcnt vmcnt(0)
	v_cmp_eq_u32_e32 vcc, v0, v3
	s_and_saveexec_b64 s[22:23], vcc
	s_cbranch_execz .LBB0_269
	s_mov_b32 s19, 1
	s_mov_b64 s[26:27], 0
	s_branch .LBB0_260

; __device__ __forceinline__ unsigned xb_ld(unsigned* q) { return __hip_atomic_load(q, __ATOMIC_RELAXED, __HIP_MEMORY_SCOPE_AGENT); }
; __device__ __forceinline__ unsigned xb_add(unsigned* q, unsigned v) { return __hip_atomic_fetch_add(q, v, __ATOMIC_RELAXED, __HIP_MEMORY_SCOPE_AGENT); }
; #define XB_SPIN(cond, bar) do { unsigned _sp = 0; while (cond) { __builtin_amdgcn_s_sleep(1); \
;     if ((++_sp & 255u) == 0u) { if (xb_ld(&(bar)[XB_TMO])) break; if (_sp > XB_SPIN_CAP) { atomicAdd(&(bar)[XB_TMO], 1u); break; } } } } while (0)
; __device__ __forceinline__ void gbar(unsigned* bar, volatile unsigned* st) {
;     ...
;     const unsigned old = xb_add(&bar[XB_XSUB(x)], 1u);
;     const unsigned gen = old / nloc;
;     if (old + 1u == (gen + 1u) * nloc) {
;       __builtin_amdgcn_fence(__ATOMIC_RELEASE, "agent");
;       asm volatile("s_waitcnt vmcnt(0)" ::: "memory");
;       const unsigned og = xb_add(&bar[XB_TOP], 1u);
;       const unsigned tg = og / nx;
;       if (og + 1u == (tg + 1u) * nx) xb_add(&bar[XB_TOPGEN], 1u);
;       else XB_SPIN(xb_ld(&bar[XB_TOPGEN]) == tg, bar);
;       __builtin_amdgcn_fence(__ATOMIC_ACQUIRE, "agent");
;       xb_add(&bar[XB_XGEN(x)], 1u);
;       asm volatile("s_waitcnt vmcnt(0)" ::: "memory");
;     } else {
;       XB_SPIN(xb_ld(&bar[XB_XGEN(x)]) == gen, bar);
.LBB0_405:
	s_or_b64 exec, exec, s[20:21]
	s_waitcnt vmcnt(0)
	v_readfirstlane_b32 s10, v20
	v_sub_u32_e32 v21, 0, v2
	s_nop 0
	v_add_u32_e32 v20, s10, v3
	v_cvt_f32_u32_e32 v3, v2
	v_rcp_iflag_f32_e32 v3, v3
	s_nop 0
	v_mul_f32_e32 v3, 0x4f7ffffe, v3
	v_cvt_u32_f32_e32 v3, v3
	v_mul_lo_u32 v21, v21, v3
	v_mul_hi_u32 v21, v3, v21
	v_add_u32_e32 v3, v3, v21
	v_mul_hi_u32 v3, v20, v3
	v_mul_lo_u32 v21, v3, v2
	v_sub_u32_e32 v21, v20, v21
	v_cmp_ge_u32_e32 vcc, v21, v2
	v_add_u32_e32 v22, 1, v3
	s_nop 0
	v_cndmask_b32_e32 v3, v3, v22, vcc
	v_sub_u32_e32 v22, v21, v2
	v_cndmask_b32_e32 v21, v21, v22, vcc
	v_cmp_ge_u32_e32 vcc, v21, v2
	v_add_u32_e32 v21, 1, v3
	v_add_u32_e32 v22, 1, v20
	v_cndmask_b32_e32 v3, v3, v21, vcc
	v_mad_u64_u32 v[20:21], s[10:11], v2, v3, v[2:3]
	v_cmp_ne_u32_e32 vcc, v22, v20
	s_and_saveexec_b64 s[10:11], vcc
	s_xor_b64 s[10:11], exec, s[10:11]
	s_cbranch_execz .LBB0_419
	s_add_u32 s22, s6, 0x3500
	s_addc_u32 s23, s7, 0
	global_load_dword v0, v1, s[22:23] sc1
	s_waitcnt vmcnt(0)
	v_cmp_eq_u32_e32 vcc, v0, v3
	s_and_saveexec_b64 s[20:21], vcc
	s_cbranch_execz .LBB0_418
	s_mov_b32 s37, 1
	s_mov_b64 s[24:25], 0
	s_branch .LBB0_409

; __device__ __forceinline__ unsigned xb_ld(unsigned* q) { return __hip_atomic_load(q, __ATOMIC_RELAXED, __HIP_MEMORY_SCOPE_AGENT); }
; __device__ __forceinline__ unsigned xb_add(unsigned* q, unsigned v) { return __hip_atomic_fetch_add(q, v, __ATOMIC_RELAXED, __HIP_MEMORY_SCOPE_AGENT); }
; #define XB_SPIN(cond, bar) do { unsigned _sp = 0; while (cond) { __builtin_amdgcn_s_sleep(1); \
;     if ((++_sp & 255u) == 0u) { if (xb_ld(&(bar)[XB_TMO])) break; if (_sp > XB_SPIN_CAP) { atomicAdd(&(bar)[XB_TMO], 1u); break; } } } } while (0)
; __device__ __forceinline__ void gbar(unsigned* bar, volatile unsigned* st) {
;     ...
;     const unsigned old = xb_add(&bar[XB_XSUB(x)], 1u);
;     const unsigned gen = old / nloc;
;     if (old + 1u == (gen + 1u) * nloc) {
;       __builtin_amdgcn_fence(__ATOMIC_RELEASE, "agent");
;       asm volatile("s_waitcnt vmcnt(0)" ::: "memory");
;       const unsigned og = xb_add(&bar[XB_TOP], 1u);
;       const unsigned tg = og / nx;
;       if (og + 1u == (tg + 1u) * nx) xb_add(&bar[XB_TOPGEN], 1u);
;       else XB_SPIN(xb_ld(&bar[XB_TOPGEN]) == tg, bar);
;       __builtin_amdgcn_fence(__ATOMIC_ACQUIRE, "agent");
;       xb_add(&bar[XB_XGEN(x)], 1u);
;       asm volatile("s_waitcnt vmcnt(0)" ::: "memory");
;     } else {
;       XB_SPIN(xb_ld(&bar[XB_XGEN(x)]) == gen, bar);
.LBB0_667:
	s_or_b64 exec, exec, s[22:23]
	s_waitcnt vmcnt(0)
	v_readfirstlane_b32 s10, v20
	v_sub_u32_e32 v21, 0, v2
	s_nop 0
	v_add_u32_e32 v20, s10, v3
	v_cvt_f32_u32_e32 v3, v2
	v_rcp_iflag_f32_e32 v3, v3
	s_nop 0
	v_mul_f32_e32 v3, 0x4f7ffffe, v3
	v_cvt_u32_f32_e32 v3, v3
	v_mul_lo_u32 v21, v21, v3
	v_mul_hi_u32 v21, v3, v21
	v_add_u32_e32 v3, v3, v21
	v_mul_hi_u32 v3, v20, v3
	v_mul_lo_u32 v21, v3, v2
	v_sub_u32_e32 v21, v20, v21
	v_cmp_ge_u32_e32 vcc, v21, v2
	v_add_u32_e32 v22, 1, v3
	s_nop 0
	v_cndmask_b32_e32 v3, v3, v22, vcc
	v_sub_u32_e32 v22, v21, v2
	v_cndmask_b32_e32 v21, v21, v22, vcc
	v_cmp_ge_u32_e32 vcc, v21, v2
	v_add_u32_e32 v21, 1, v3
	v_add_u32_e32 v22, 1, v20
	v_cndmask_b32_e32 v3, v3, v21, vcc
	v_mad_u64_u32 v[20:21], s[10:11], v2, v3, v[2:3]
	v_cmp_ne_u32_e32 vcc, v22, v20
	s_and_saveexec_b64 s[10:11], vcc
	s_xor_b64 s[10:11], exec, s[10:11]
	s_cbranch_execz .LBB0_681
	s_add_u32 s24, s6, 0x3500
	s_addc_u32 s25, s7, 0
	global_load_dword v0, v1, s[24:25] sc1
	s_waitcnt vmcnt(0)
	v_cmp_eq_u32_e32 vcc, v0, v3
	s_and_saveexec_b64 s[22:23], vcc
	s_cbranch_execz .LBB0_680
	s_mov_b32 s19, 1
	s_mov_b64 s[26:27], 0
	s_branch .LBB0_671

; __device__ __forceinline__ unsigned xb_ld(unsigned* q) { return __hip_atomic_load(q, __ATOMIC_RELAXED, __HIP_MEMORY_SCOPE_AGENT); }
; __device__ __forceinline__ unsigned xb_add(unsigned* q, unsigned v) { return __hip_atomic_fetch_add(q, v, __ATOMIC_RELAXED, __HIP_MEMORY_SCOPE_AGENT); }
; #define XB_SPIN(cond, bar) do { unsigned _sp = 0; while (cond) { __builtin_amdgcn_s_sleep(1); \
;     if ((++_sp & 255u) == 0u) { if (xb_ld(&(bar)[XB_TMO])) break; if (_sp > XB_SPIN_CAP) { atomicAdd(&(bar)[XB_TMO], 1u); break; } } } } while (0)
; __device__ __forceinline__ void gbar(unsigned* bar, volatile unsigned* st) {
;     ...
;     const unsigned old = xb_add(&bar[XB_XSUB(x)], 1u);
;     const unsigned gen = old / nloc;
;     if (old + 1u == (gen + 1u) * nloc) {
;       __builtin_amdgcn_fence(__ATOMIC_RELEASE, "agent");
;       asm volatile("s_waitcnt vmcnt(0)" ::: "memory");
;       const unsigned og = xb_add(&bar[XB_TOP], 1u);
;       const unsigned tg = og / nx;
;       if (og + 1u == (tg + 1u) * nx) xb_add(&bar[XB_TOPGEN], 1u);
;       else XB_SPIN(xb_ld(&bar[XB_TOPGEN]) == tg, bar);
;       __builtin_amdgcn_fence(__ATOMIC_ACQUIRE, "agent");
;       xb_add(&bar[XB_XGEN(x)], 1u);
;       asm volatile("s_waitcnt vmcnt(0)" ::: "memory");
;     } else {
;       XB_SPIN(xb_ld(&bar[XB_XGEN(x)]) == gen, bar);
.LBB0_722:
	s_or_b64 exec, exec, s[20:21]
	s_waitcnt vmcnt(0)
	v_readfirstlane_b32 s10, v20
	v_sub_u32_e32 v21, 0, v2
	s_nop 0
	v_add_u32_e32 v20, s10, v3
	v_cvt_f32_u32_e32 v3, v2
	v_rcp_iflag_f32_e32 v3, v3
	s_nop 0
	v_mul_f32_e32 v3, 0x4f7ffffe, v3
	v_cvt_u32_f32_e32 v3, v3
	v_mul_lo_u32 v21, v21, v3
	v_mul_hi_u32 v21, v3, v21
	v_add_u32_e32 v3, v3, v21
	v_mul_hi_u32 v3, v20, v3
	v_mul_lo_u32 v21, v3, v2
	v_sub_u32_e32 v21, v20, v21
	v_cmp_ge_u32_e32 vcc, v21, v2
	v_add_u32_e32 v22, 1, v3
	s_nop 0
	v_cndmask_b32_e32 v3, v3, v22, vcc
	v_sub_u32_e32 v22, v21, v2
	v_cndmask_b32_e32 v21, v21, v22, vcc
	v_cmp_ge_u32_e32 vcc, v21, v2
	v_add_u32_e32 v21, 1, v3
	v_add_u32_e32 v22, 1, v20
	v_cndmask_b32_e32 v3, v3, v21, vcc
	v_mad_u64_u32 v[20:21], s[10:11], v2, v3, v[2:3]
	v_cmp_ne_u32_e32 vcc, v22, v20
	s_and_saveexec_b64 s[10:11], vcc
	s_xor_b64 s[10:11], exec, s[10:11]
	s_cbranch_execz .LBB0_736
	s_add_u32 s22, s6, 0x3500
	s_addc_u32 s23, s7, 0
	global_load_dword v0, v1, s[22:23] sc1
	s_waitcnt vmcnt(0)
	v_cmp_eq_u32_e32 vcc, v0, v3
	s_and_saveexec_b64 s[20:21], vcc
	s_cbranch_execz .LBB0_735
	s_mov_b32 s19, 1
	s_mov_b64 s[24:25], 0
	s_branch .LBB0_726

; __device__ __forceinline__ unsigned xb_ld(unsigned* q) { return __hip_atomic_load(q, __ATOMIC_RELAXED, __HIP_MEMORY_SCOPE_AGENT); }
; __device__ __forceinline__ unsigned xb_add(unsigned* q, unsigned v) { return __hip_atomic_fetch_add(q, v, __ATOMIC_RELAXED, __HIP_MEMORY_SCOPE_AGENT); }
; #define XB_SPIN(cond, bar) do { unsigned _sp = 0; while (cond) { __builtin_amdgcn_s_sleep(1); \
;     if ((++_sp & 255u) == 0u) { if (xb_ld(&(bar)[XB_TMO])) break; if (_sp > XB_SPIN_CAP) { atomicAdd(&(bar)[XB_TMO], 1u); break; } } } } while (0)
; __device__ __forceinline__ void gbar(unsigned* bar, volatile unsigned* st) {
;     ...
;     const unsigned old = xb_add(&bar[XB_XSUB(x)], 1u);
;     const unsigned gen = old / nloc;
;     if (old + 1u == (gen + 1u) * nloc) {
;       __builtin_amdgcn_fence(__ATOMIC_RELEASE, "agent");
;       asm volatile("s_waitcnt vmcnt(0)" ::: "memory");
;       const unsigned og = xb_add(&bar[XB_TOP], 1u);
;       const unsigned tg = og / nx;
;       if (og + 1u == (tg + 1u) * nx) xb_add(&bar[XB_TOPGEN], 1u);
;       else XB_SPIN(xb_ld(&bar[XB_TOPGEN]) == tg, bar);
;       __builtin_amdgcn_fence(__ATOMIC_ACQUIRE, "agent");
;       xb_add(&bar[XB_XGEN(x)], 1u);
;       asm volatile("s_waitcnt vmcnt(0)" ::: "memory");
;     } else {
;       XB_SPIN(xb_ld(&bar[XB_XGEN(x)]) == gen, bar);
.LBB0_839:
	s_or_b64 exec, exec, s[18:19]
	s_waitcnt vmcnt(0)
	v_readfirstlane_b32 s10, v20
	v_sub_u32_e32 v21, 0, v2
	s_nop 0
	v_add_u32_e32 v20, s10, v3
	v_cvt_f32_u32_e32 v3, v2
	v_rcp_iflag_f32_e32 v3, v3
	s_nop 0
	v_mul_f32_e32 v3, 0x4f7ffffe, v3
	v_cvt_u32_f32_e32 v3, v3
	v_mul_lo_u32 v21, v21, v3
	v_mul_hi_u32 v21, v3, v21
	v_add_u32_e32 v3, v3, v21
	v_mul_hi_u32 v3, v20, v3
	v_mul_lo_u32 v21, v3, v2
	v_sub_u32_e32 v21, v20, v21
	v_cmp_ge_u32_e32 vcc, v21, v2
	v_add_u32_e32 v22, 1, v3
	s_nop 0
	v_cndmask_b32_e32 v3, v3, v22, vcc
	v_sub_u32_e32 v22, v21, v2
	v_cndmask_b32_e32 v21, v21, v22, vcc
	v_cmp_ge_u32_e32 vcc, v21, v2
	v_add_u32_e32 v21, 1, v3
	v_add_u32_e32 v22, 1, v20
	v_cndmask_b32_e32 v3, v3, v21, vcc
	v_mad_u64_u32 v[20:21], s[10:11], v2, v3, v[2:3]
	v_cmp_ne_u32_e32 vcc, v22, v20
	s_and_saveexec_b64 s[10:11], vcc
	s_xor_b64 s[10:11], exec, s[10:11]
	s_cbranch_execz .LBB0_853
	s_add_u32 s20, s6, 0x3500
	s_addc_u32 s21, s7, 0
	global_load_dword v0, v1, s[20:21] sc1
	s_waitcnt vmcnt(0)
	v_cmp_eq_u32_e32 vcc, v0, v3
	s_and_saveexec_b64 s[18:19], vcc
	s_cbranch_execz .LBB0_852
	s_mov_b32 s34, 1
	s_mov_b64 s[22:23], 0
	s_branch .LBB0_843

; __device__ __forceinline__ unsigned xb_ld(unsigned* q) { return __hip_atomic_load(q, __ATOMIC_RELAXED, __HIP_MEMORY_SCOPE_AGENT); }
; __device__ __forceinline__ unsigned xb_add(unsigned* q, unsigned v) { return __hip_atomic_fetch_add(q, v, __ATOMIC_RELAXED, __HIP_MEMORY_SCOPE_AGENT); }
; #define XB_SPIN(cond, bar) do { unsigned _sp = 0; while (cond) { __builtin_amdgcn_s_sleep(1); \
;     if ((++_sp & 255u) == 0u) { if (xb_ld(&(bar)[XB_TMO])) break; if (_sp > XB_SPIN_CAP) { atomicAdd(&(bar)[XB_TMO], 1u); break; } } } } while (0)
; __device__ __forceinline__ void gbar(unsigned* bar, volatile unsigned* st) {
;     ...
;     const unsigned old = xb_add(&bar[XB_XSUB(x)], 1u);
;     const unsigned gen = old / nloc;
;     if (old + 1u == (gen + 1u) * nloc) {
;       __builtin_amdgcn_fence(__ATOMIC_RELEASE, "agent");
;       asm volatile("s_waitcnt vmcnt(0)" ::: "memory");
;       const unsigned og = xb_add(&bar[XB_TOP], 1u);
;       const unsigned tg = og / nx;
;       if (og + 1u == (tg + 1u) * nx) xb_add(&bar[XB_TOPGEN], 1u);
;       else XB_SPIN(xb_ld(&bar[XB_TOPGEN]) == tg, bar);
;       __builtin_amdgcn_fence(__ATOMIC_ACQUIRE, "agent");
;       xb_add(&bar[XB_XGEN(x)], 1u);
;       asm volatile("s_waitcnt vmcnt(0)" ::: "memory");
;     } else {
;       XB_SPIN(xb_ld(&bar[XB_XGEN(x)]) == gen, bar);
.LBB0_907:
	s_or_b64 exec, exec, s[18:19]
	s_waitcnt vmcnt(0)
	v_readfirstlane_b32 s16, v20
	v_sub_u32_e32 v21, 0, v2
	s_nop 0
	v_add_u32_e32 v20, s16, v3
	v_cvt_f32_u32_e32 v3, v2
	v_rcp_iflag_f32_e32 v3, v3
	s_nop 0
	v_mul_f32_e32 v3, 0x4f7ffffe, v3
	v_cvt_u32_f32_e32 v3, v3
	v_mul_lo_u32 v21, v21, v3
	v_mul_hi_u32 v21, v3, v21
	v_add_u32_e32 v3, v3, v21
	v_mul_hi_u32 v3, v20, v3
	v_mul_lo_u32 v21, v3, v2
	v_sub_u32_e32 v21, v20, v21
	v_cmp_ge_u32_e32 vcc, v21, v2
	v_add_u32_e32 v22, 1, v3
	s_nop 0
	v_cndmask_b32_e32 v3, v3, v22, vcc
	v_sub_u32_e32 v22, v21, v2
	v_cndmask_b32_e32 v21, v21, v22, vcc
	v_cmp_ge_u32_e32 vcc, v21, v2
	v_add_u32_e32 v21, 1, v3
	v_add_u32_e32 v22, 1, v20
	v_cndmask_b32_e32 v3, v3, v21, vcc
	v_mad_u64_u32 v[20:21], s[16:17], v2, v3, v[2:3]
	v_cmp_ne_u32_e32 vcc, v22, v20
	s_and_saveexec_b64 s[16:17], vcc
	s_xor_b64 s[16:17], exec, s[16:17]
	s_cbranch_execz .LBB0_921
	s_add_u32 s20, s6, 0x3500
	s_addc_u32 s21, s7, 0
	global_load_dword v0, v1, s[20:21] sc1
	s_waitcnt vmcnt(0)
	v_cmp_eq_u32_e32 vcc, v0, v3
	s_and_saveexec_b64 s[18:19], vcc
	s_cbranch_execz .LBB0_920
	s_mov_b32 s34, 1
	s_mov_b64 s[22:23], 0
	s_branch .LBB0_911

; __device__ __forceinline__ unsigned xb_ld(unsigned* q) { return __hip_atomic_load(q, __ATOMIC_RELAXED, __HIP_MEMORY_SCOPE_AGENT); }
; __device__ __forceinline__ unsigned xb_add(unsigned* q, unsigned v) { return __hip_atomic_fetch_add(q, v, __ATOMIC_RELAXED, __HIP_MEMORY_SCOPE_AGENT); }
; #define XB_SPIN(cond, bar) do { unsigned _sp = 0; while (cond) { __builtin_amdgcn_s_sleep(1); \
;     if ((++_sp & 255u) == 0u) { if (xb_ld(&(bar)[XB_TMO])) break; if (_sp > XB_SPIN_CAP) { atomicAdd(&(bar)[XB_TMO], 1u); break; } } } } while (0)
; __device__ __forceinline__ void gbar(unsigned* bar, volatile unsigned* st) {
;     ...
;     const unsigned old = xb_add(&bar[XB_XSUB(x)], 1u);
;     const unsigned gen = old / nloc;
;     if (old + 1u == (gen + 1u) * nloc) {
;       __builtin_amdgcn_fence(__ATOMIC_RELEASE, "agent");
;       asm volatile("s_waitcnt vmcnt(0)" ::: "memory");
;       const unsigned og = xb_add(&bar[XB_TOP], 1u);
;       const unsigned tg = og / nx;
;       if (og + 1u == (tg + 1u) * nx) xb_add(&bar[XB_TOPGEN], 1u);
;       else XB_SPIN(xb_ld(&bar[XB_TOPGEN]) == tg, bar);
;       __builtin_amdgcn_fence(__ATOMIC_ACQUIRE, "agent");
;       xb_add(&bar[XB_XGEN(x)], 1u);
;       asm volatile("s_waitcnt vmcnt(0)" ::: "memory");
;     } else {
;       XB_SPIN(xb_ld(&bar[XB_XGEN(x)]) == gen, bar);
.LBB0_964:
	s_or_b64 exec, exec, s[12:13]
	s_waitcnt vmcnt(0)
	v_readfirstlane_b32 s10, v20
	v_sub_u32_e32 v21, 0, v2
	s_nop 0
	v_add_u32_e32 v20, s10, v3
	v_cvt_f32_u32_e32 v3, v2
	v_rcp_iflag_f32_e32 v3, v3
	s_nop 0
	v_mul_f32_e32 v3, 0x4f7ffffe, v3
	v_cvt_u32_f32_e32 v3, v3
	v_mul_lo_u32 v21, v21, v3
	v_mul_hi_u32 v21, v3, v21
	v_add_u32_e32 v3, v3, v21
	v_mul_hi_u32 v3, v20, v3
	v_mul_lo_u32 v21, v3, v2
	v_sub_u32_e32 v21, v20, v21
	v_cmp_ge_u32_e32 vcc, v21, v2
	v_add_u32_e32 v22, 1, v3
	s_nop 0
	v_cndmask_b32_e32 v3, v3, v22, vcc
	v_sub_u32_e32 v22, v21, v2
	v_cndmask_b32_e32 v21, v21, v22, vcc
	v_cmp_ge_u32_e32 vcc, v21, v2
	v_add_u32_e32 v21, 1, v3
	v_add_u32_e32 v22, 1, v20
	v_cndmask_b32_e32 v3, v3, v21, vcc
	v_mad_u64_u32 v[20:21], s[10:11], v2, v3, v[2:3]
	v_cmp_ne_u32_e32 vcc, v22, v20
	s_and_saveexec_b64 s[10:11], vcc
	s_xor_b64 s[10:11], exec, s[10:11]
	s_cbranch_execz .LBB0_978
	s_add_u32 s14, s6, 0x3500
	s_addc_u32 s15, s7, 0
	global_load_dword v0, v1, s[14:15] sc1
	s_waitcnt vmcnt(0)
	v_cmp_eq_u32_e32 vcc, v0, v3
	s_and_saveexec_b64 s[12:13], vcc
	s_cbranch_execz .LBB0_977
	s_mov_b32 s26, 1
	s_mov_b64 s[16:17], 0
	s_branch .LBB0_968
